# G2b tile redistribution: partners (bid 256..287) of the 32 three-item MOUT blocks take no G2b tiles, other 448 blocks stride the tiles
# baseline (speedup 1.0000x reference)
.LBB1_806:
	s_mov_b32 s59, 0
	v_readlane_b32 s2, v242, 62
	s_cmp_ge_i32 s56, s2
	s_cselect_b64 s[4:5], -1, 0
	s_sub_i32 s2, s56, s2
	s_cmpk_lt_u32 s56, 0x100
	s_cbranch_scc1 .Lg2b_idx_ok
	s_sub_i32 s2, s2, 32
	s_cmpk_lt_u32 s56, 0x120
	s_cbranch_scc0 .Lg2b_idx_ok
	s_movk_i32 s2, 0x7fff
.Lg2b_idx_ok:
	s_load_dwordx2 s[56:57], s[0:1], 0x1b8
	s_load_dwordx16 s[64:79], s[0:1], 0x100
	s_cmpk_lt_i32 s2, 0x580
	s_cselect_b64 s[6:7], -1, 0
	s_and_b64 s[4:5], s[4:5], s[6:7]
	v_readlane_b32 s14, v241, 36
	s_andn2_b64 vcc, exec, s[4:5]
	v_readlane_b32 s15, v241, 37
	s_cbranch_vccnz .LBB1_810

.LBB1_808:
	s_lshl_b32 s19, s18, 8
	s_add_i32 s19, s19, 0x80
	s_min_u32 s19, s19, 0x780
	s_add_u32 s40, s8, s19
	s_addc_u32 s41, s9, 0
	s_add_u32 s42, s10, s19
	s_addc_u32 s43, s11, 0
	ds_read_b128 v[142:145], v234 offset:0
	ds_read_b128 v[146:149], v234 offset:2048
	ds_read_b128 v[150:153], v234 offset:4096
	ds_read_b128 v[154:157], v234 offset:6144
	ds_read_b128 v[130:133], v232 offset:0
	ds_read_b128 v[134:137], v232 offset:2048
	ds_read_b128 v[138:141], v232 offset:4096
	ds_read_b128 v[216:219], v235 offset:0
	ds_read_b128 v[220:223], v235 offset:2048
	ds_read_b128 v[224:227], v235 offset:4096
	ds_read_b128 v[228:231], v235 offset:6144
	ds_read_b128 v[188:191], v233 offset:0
	ds_read_b128 v[192:195], v233 offset:2048
	ds_read_b128 v[196:199], v233 offset:4096
	s_waitcnt lgkmcnt(9)
	s_add_i32 m0, s16, 0x7010
	s_nop 0
	v_mfma_f32_16x16x32_bf16 v[72:75], v[142:145], v[130:133], v[72:75]
	global_load_lds_dwordx4 v238, s[40:41]
	s_add_i32 m0, s16, 0x7410
	s_add_u32 s12, s40, 0x4000
	s_addc_u32 s13, s41, 0
	v_mfma_f32_16x16x32_bf16 v[40:43], v[146:149], v[130:133], v[40:43]
	global_load_lds_dwordx4 v239, s[12:13]
	v_mfma_f32_16x16x32_bf16 v[36:39], v[150:153], v[130:133], v[36:39]
	v_mfma_f32_16x16x32_bf16 v[32:35], v[154:157], v[130:133], v[32:35]
	s_waitcnt lgkmcnt(8)
	s_add_i32 m0, s16, 0x7810
	s_add_u32 s12, s40, 0x8000
	s_addc_u32 s13, s41, 0
	v_mfma_f32_16x16x32_bf16 v[28:31], v[142:145], v[134:137], v[28:31]
	v_mfma_f32_16x16x32_bf16 v[24:27], v[146:149], v[134:137], v[24:27]
	global_load_lds_dwordx4 v238, s[12:13]
	v_mfma_f32_16x16x32_bf16 v[20:23], v[150:153], v[134:137], v[20:23]
	v_mfma_f32_16x16x32_bf16 v[16:19], v[154:157], v[134:137], v[16:19]
	s_waitcnt lgkmcnt(7)
	s_add_i32 m0, s17, 0xa010
	s_nop 0
	v_mfma_f32_16x16x32_bf16 v[12:15], v[142:145], v[138:141], v[12:15]
	v_mfma_f32_16x16x32_bf16 v[8:11], v[146:149], v[138:141], v[8:11]
	global_load_lds_dwordx4 v236, s[42:43]
	v_mfma_f32_16x16x32_bf16 v[4:7], v[150:153], v[138:141], v[4:7]
	v_mfma_f32_16x16x32_bf16 v[0:3], v[154:157], v[138:141], v[0:3]
	s_waitcnt lgkmcnt(2)
	s_add_i32 m0, s17, 0xa410
	s_add_u32 s12, s42, 0x4000
	s_addc_u32 s13, s43, 0
	v_mfma_f32_16x16x32_bf16 v[72:75], v[216:219], v[188:191], v[72:75]
	v_mfma_f32_16x16x32_bf16 v[40:43], v[220:223], v[188:191], v[40:43]
	global_load_lds_dwordx4 v237, s[12:13]
	v_mfma_f32_16x16x32_bf16 v[36:39], v[224:227], v[188:191], v[36:39]
	v_mfma_f32_16x16x32_bf16 v[32:35], v[228:231], v[188:191], v[32:35]
	s_waitcnt lgkmcnt(1)
	s_add_i32 m0, s17, 0xa810
	s_add_u32 s12, s42, 0x8000
	s_addc_u32 s13, s43, 0
	v_mfma_f32_16x16x32_bf16 v[28:31], v[216:219], v[192:195], v[28:31]
	v_mfma_f32_16x16x32_bf16 v[24:27], v[220:223], v[192:195], v[24:27]
	global_load_lds_dwordx4 v236, s[12:13]
	v_mfma_f32_16x16x32_bf16 v[20:23], v[224:227], v[192:195], v[20:23]
	v_mfma_f32_16x16x32_bf16 v[16:19], v[228:231], v[192:195], v[16:19]
	s_waitcnt lgkmcnt(0)
	s_add_i32 m0, s17, 0xac10
	s_add_u32 s12, s42, 0xc000
	s_addc_u32 s13, s43, 0
	v_mfma_f32_16x16x32_bf16 v[12:15], v[216:219], v[196:199], v[12:15]
	v_mfma_f32_16x16x32_bf16 v[8:11], v[220:223], v[196:199], v[8:11]
	global_load_lds_dwordx4 v237, s[12:13]
	v_mfma_f32_16x16x32_bf16 v[4:7], v[224:227], v[196:199], v[4:7]
	v_mfma_f32_16x16x32_bf16 v[0:3], v[228:231], v[196:199], v[0:3]
	s_waitcnt vmcnt(0)
	s_barrier
	s_lshl_b32 s19, s18, 8
	s_add_i32 s19, s19, 0x100
	s_min_u32 s19, s19, 0x780
	s_add_u32 s40, s8, s19
	s_addc_u32 s41, s9, 0
	s_add_u32 s42, s10, s19
	s_addc_u32 s43, s11, 0
	ds_read_b128 v[142:145], v234 offset:28672
	ds_read_b128 v[146:149], v234 offset:30720
	ds_read_b128 v[150:153], v234 offset:32768
	ds_read_b128 v[154:157], v234 offset:34816
	ds_read_b128 v[130:133], v232 offset:28672
	ds_read_b128 v[134:137], v232 offset:30720
	ds_read_b128 v[138:141], v232 offset:32768
	ds_read_b128 v[216:219], v235 offset:28672
	ds_read_b128 v[220:223], v235 offset:30720
	ds_read_b128 v[224:227], v235 offset:32768
	ds_read_b128 v[228:231], v235 offset:34816
	ds_read_b128 v[188:191], v233 offset:28672
	ds_read_b128 v[192:195], v233 offset:30720
	ds_read_b128 v[196:199], v233 offset:32768
	s_waitcnt lgkmcnt(9)
	s_add_i32 m0, s16, 0x10
	s_nop 0
	v_mfma_f32_16x16x32_bf16 v[72:75], v[142:145], v[130:133], v[72:75]
	global_load_lds_dwordx4 v238, s[40:41]
	s_add_i32 m0, s16, 0x410
	s_add_u32 s12, s40, 0x4000
	s_addc_u32 s13, s41, 0
	v_mfma_f32_16x16x32_bf16 v[40:43], v[146:149], v[130:133], v[40:43]
	global_load_lds_dwordx4 v239, s[12:13]
	v_mfma_f32_16x16x32_bf16 v[36:39], v[150:153], v[130:133], v[36:39]
	v_mfma_f32_16x16x32_bf16 v[32:35], v[154:157], v[130:133], v[32:35]
	s_waitcnt lgkmcnt(8)
	s_add_i32 m0, s16, 0x810
	s_add_u32 s12, s40, 0x8000
	s_addc_u32 s13, s41, 0
	v_mfma_f32_16x16x32_bf16 v[28:31], v[142:145], v[134:137], v[28:31]
	v_mfma_f32_16x16x32_bf16 v[24:27], v[146:149], v[134:137], v[24:27]
	global_load_lds_dwordx4 v238, s[12:13]
	v_mfma_f32_16x16x32_bf16 v[20:23], v[150:153], v[134:137], v[20:23]
	v_mfma_f32_16x16x32_bf16 v[16:19], v[154:157], v[134:137], v[16:19]
	s_waitcnt lgkmcnt(7)
	s_add_i32 m0, s17, 0x3010
	s_nop 0
	v_mfma_f32_16x16x32_bf16 v[12:15], v[142:145], v[138:141], v[12:15]
	v_mfma_f32_16x16x32_bf16 v[8:11], v[146:149], v[138:141], v[8:11]
	global_load_lds_dwordx4 v236, s[42:43]
	v_mfma_f32_16x16x32_bf16 v[4:7], v[150:153], v[138:141], v[4:7]
	v_mfma_f32_16x16x32_bf16 v[0:3], v[154:157], v[138:141], v[0:3]
	s_waitcnt lgkmcnt(2)
	s_add_i32 m0, s17, 0x3410
	s_add_u32 s12, s42, 0x4000
	s_addc_u32 s13, s43, 0
	v_mfma_f32_16x16x32_bf16 v[72:75], v[216:219], v[188:191], v[72:75]
	v_mfma_f32_16x16x32_bf16 v[40:43], v[220:223], v[188:191], v[40:43]
	global_load_lds_dwordx4 v237, s[12:13]
	v_mfma_f32_16x16x32_bf16 v[36:39], v[224:227], v[188:191], v[36:39]
	v_mfma_f32_16x16x32_bf16 v[32:35], v[228:231], v[188:191], v[32:35]
	s_waitcnt lgkmcnt(1)
	s_add_i32 m0, s17, 0x3810
	s_add_u32 s12, s42, 0x8000
	s_addc_u32 s13, s43, 0
	v_mfma_f32_16x16x32_bf16 v[28:31], v[216:219], v[192:195], v[28:31]
	v_mfma_f32_16x16x32_bf16 v[24:27], v[220:223], v[192:195], v[24:27]
	global_load_lds_dwordx4 v236, s[12:13]
	v_mfma_f32_16x16x32_bf16 v[20:23], v[224:227], v[192:195], v[20:23]
	v_mfma_f32_16x16x32_bf16 v[16:19], v[228:231], v[192:195], v[16:19]
	s_waitcnt lgkmcnt(0)
	s_add_i32 m0, s17, 0x3c10
	s_add_u32 s12, s42, 0xc000
	s_addc_u32 s13, s43, 0
	v_mfma_f32_16x16x32_bf16 v[12:15], v[216:219], v[196:199], v[12:15]
	v_mfma_f32_16x16x32_bf16 v[8:11], v[220:223], v[196:199], v[8:11]
	global_load_lds_dwordx4 v237, s[12:13]
	v_mfma_f32_16x16x32_bf16 v[4:7], v[224:227], v[196:199], v[4:7]
	v_mfma_f32_16x16x32_bf16 v[0:3], v[228:231], v[196:199], v[0:3]
	s_waitcnt vmcnt(0)
	s_barrier
	s_add_i32 s18, s18, 1
	s_cmp_eq_u32 s18, 8
	s_cbranch_scc0 .LBB1_808
	s_setprio 0
	s_waitcnt vmcnt(0)
	s_movk_i32 s30, 0x1c0
	s_nop 1
	s_add_i32 s31, s2, s30
	s_cmp_lt_u32 s31, 0x580
	s_cselect_b32 s59, 1, 0
	s_cbranch_scc0 .Lg96pf_none_g2b
	s_mul_i32 s38, s31, 745
	s_lshr_b32 s38, s38, 17
	s_mul_i32 s39, s38, 176
	s_sub_i32 s39, s31, s39
	s_mul_i32 s30, s39, 96
	s_sub_i32 s30, s30, s5
	s_ashr_i32 s31, s30, 31
	s_lshl_b64 s[30:31], s[30:31], 11
	s_add_u32 s88, s8, s30
	s_addc_u32 s89, s9, s31
	s_lshl_b32 s24, s38, 7
	s_sub_i32 s24, s24, s4
	s_ashr_i32 s25, s24, 31
	s_lshl_b64 s[24:25], s[24:25], 11
	s_add_u32 s90, s10, s24
	s_addc_u32 s91, s11, s25
	s_add_i32 m0, s16, 0x10
	s_nop 0
	global_load_lds_dwordx4 v238, s[88:89]
	s_add_i32 m0, s16, 0x410
	s_add_u32 s30, s88, 0x4000
	s_addc_u32 s31, s89, 0
	global_load_lds_dwordx4 v239, s[30:31]
	s_add_i32 m0, s16, 0x810
	s_add_u32 s30, s88, 0x8000
	s_addc_u32 s31, s89, 0
	global_load_lds_dwordx4 v238, s[30:31]
	s_add_i32 m0, s17, 0x3010
	s_nop 0
	global_load_lds_dwordx4 v236, s[90:91]
	s_add_i32 m0, s17, 0x3410
	s_add_u32 s30, s90, 0x4000
	s_addc_u32 s31, s91, 0
	global_load_lds_dwordx4 v237, s[30:31]
	s_add_i32 m0, s17, 0x3810
	s_add_u32 s30, s90, 0x8000
	s_addc_u32 s31, s91, 0
	global_load_lds_dwordx4 v236, s[30:31]
	s_add_i32 m0, s17, 0x3c10
	s_add_u32 s30, s90, 0xc000
	s_addc_u32 s31, s91, 0
	global_load_lds_dwordx4 v237, s[30:31]
.Lg96pf_none_g2b:
	v_and_b32_e32 v154, 15, v168
	v_lshrrev_b32_e32 v155, 4, v168
	v_lshrrev_b32_e32 v156, 7, v162
	v_bfe_u32 v157, v162, 6, 1
	v_mul_u32_u24_e32 v156, 48, v156
	v_add3_u32 v156, v156, v154, s5
	v_lshlrev_b32_e32 v157, 6, v157
	v_lshl_add_u32 v157, v155, 2, v157
	v_add_u32_e32 v157, s4, v157
	v_lshlrev_b32_e32 v53, 2, v157
	v_lshlrev_b32_e32 v158, 1, v157
	v_lshl_add_u32 v44, v156, 14, v158
	v_lshl_add_u32 v47, v156, 12, v53
	v_add_u32_e32 v156, 16, v156
	v_lshlrev_b32_e32 v158, 1, v157
	v_lshl_add_u32 v45, v156, 14, v158
	v_lshl_add_u32 v48, v156, 12, v53
	v_add_u32_e32 v156, 16, v156
	v_lshlrev_b32_e32 v158, 1, v157
	v_lshl_add_u32 v46, v156, 14, v158
	v_lshl_add_u32 v49, v156, 12, v53
	s_add_u32 s10, s76, 0x3800
	s_addc_u32 s11, s77, 0
	global_load_dwordx4 v[54:57], v53, s[14:15] offset:0
	global_load_dwordx4 v[58:61], v53, s[14:15] offset:64
	global_load_dwordx4 v[62:65], v53, s[14:15] offset:128
	global_load_dwordx4 v[66:69], v53, s[14:15] offset:192
	global_load_dwordx2 v[188:189], v44, s[10:11] offset:0
	global_load_dwordx2 v[190:191], v44, s[10:11] offset:32
	global_load_dwordx2 v[192:193], v44, s[10:11] offset:64
	global_load_dwordx2 v[194:195], v44, s[10:11] offset:96
	global_load_dwordx2 v[196:197], v45, s[10:11] offset:0
	global_load_dwordx2 v[198:199], v45, s[10:11] offset:32
	global_load_dwordx2 v[200:201], v45, s[10:11] offset:64
	global_load_dwordx2 v[202:203], v45, s[10:11] offset:96
	global_load_dwordx2 v[204:205], v46, s[10:11] offset:0
	global_load_dwordx2 v[206:207], v46, s[10:11] offset:32
	global_load_dwordx2 v[208:209], v46, s[10:11] offset:64
	global_load_dwordx2 v[210:211], v46, s[10:11] offset:96
	s_waitcnt vmcnt(11)
	v_lshlrev_b32_e32 v150, 16, v188
	v_and_b32_e32 v151, 0xffff0000, v188
	v_lshlrev_b32_e32 v152, 16, v189
	v_and_b32_e32 v153, 0xffff0000, v189
	v_pk_add_f32 v[150:151], v[54:55], v[150:151]
	v_pk_add_f32 v[152:153], v[56:57], v[152:153]
	s_nop 0
	v_mul_f32_e32 v150, 0xbfb8aa3b, v150
	v_mul_f32_e32 v151, 0xbfb8aa3b, v151
	v_mul_f32_e32 v152, 0xbfb8aa3b, v152
	v_mul_f32_e32 v153, 0xbfb8aa3b, v153
	v_exp_f32_e32 v150, v150
	v_exp_f32_e32 v151, v151
	v_exp_f32_e32 v152, v152
	v_exp_f32_e32 v153, v153
	v_add_f32_e32 v150, 1.0, v150
	v_add_f32_e32 v151, 1.0, v151
	v_add_f32_e32 v152, 1.0, v152
	v_add_f32_e32 v153, 1.0, v153
	v_rcp_f32_e32 v150, v150
	v_rcp_f32_e32 v151, v151
	v_rcp_f32_e32 v152, v152
	v_rcp_f32_e32 v153, v153
	v_pk_mul_f32 v[72:73], v[72:73], v[150:151]
	v_pk_mul_f32 v[74:75], v[74:75], v[152:153]
	s_nop 0
	global_store_dwordx4 v47, v[72:75], s[72:73] offset:0
	s_waitcnt vmcnt(10)
	v_lshlrev_b32_e32 v150, 16, v190
	v_and_b32_e32 v151, 0xffff0000, v190
	v_lshlrev_b32_e32 v152, 16, v191
	v_and_b32_e32 v153, 0xffff0000, v191
	v_pk_add_f32 v[150:151], v[58:59], v[150:151]
	v_pk_add_f32 v[152:153], v[60:61], v[152:153]
	s_nop 0
	v_mul_f32_e32 v150, 0xbfb8aa3b, v150
	v_mul_f32_e32 v151, 0xbfb8aa3b, v151
	v_mul_f32_e32 v152, 0xbfb8aa3b, v152
	v_mul_f32_e32 v153, 0xbfb8aa3b, v153
	v_exp_f32_e32 v150, v150
	v_exp_f32_e32 v151, v151
	v_exp_f32_e32 v152, v152
	v_exp_f32_e32 v153, v153
	v_add_f32_e32 v150, 1.0, v150
	v_add_f32_e32 v151, 1.0, v151
	v_add_f32_e32 v152, 1.0, v152
	v_add_f32_e32 v153, 1.0, v153
	v_rcp_f32_e32 v150, v150
	v_rcp_f32_e32 v151, v151
	v_rcp_f32_e32 v152, v152
	v_rcp_f32_e32 v153, v153
	v_pk_mul_f32 v[40:41], v[40:41], v[150:151]
	v_pk_mul_f32 v[42:43], v[42:43], v[152:153]
	s_nop 0
	global_store_dwordx4 v47, v[40:43], s[72:73] offset:64
	s_waitcnt vmcnt(9)
	v_lshlrev_b32_e32 v150, 16, v192
	v_and_b32_e32 v151, 0xffff0000, v192
	v_lshlrev_b32_e32 v152, 16, v193
	v_and_b32_e32 v153, 0xffff0000, v193
	v_pk_add_f32 v[150:151], v[62:63], v[150:151]
	v_pk_add_f32 v[152:153], v[64:65], v[152:153]
	s_nop 0
	v_mul_f32_e32 v150, 0xbfb8aa3b, v150
	v_mul_f32_e32 v151, 0xbfb8aa3b, v151
	v_mul_f32_e32 v152, 0xbfb8aa3b, v152
	v_mul_f32_e32 v153, 0xbfb8aa3b, v153
	v_exp_f32_e32 v150, v150
	v_exp_f32_e32 v151, v151
	v_exp_f32_e32 v152, v152
	v_exp_f32_e32 v153, v153
	v_add_f32_e32 v150, 1.0, v150
	v_add_f32_e32 v151, 1.0, v151
	v_add_f32_e32 v152, 1.0, v152
	v_add_f32_e32 v153, 1.0, v153
	v_rcp_f32_e32 v150, v150
	v_rcp_f32_e32 v151, v151
	v_rcp_f32_e32 v152, v152
	v_rcp_f32_e32 v153, v153
	v_pk_mul_f32 v[36:37], v[36:37], v[150:151]
	v_pk_mul_f32 v[38:39], v[38:39], v[152:153]
	s_nop 0
	global_store_dwordx4 v47, v[36:39], s[72:73] offset:128
	s_waitcnt vmcnt(8)
	v_lshlrev_b32_e32 v150, 16, v194
	v_and_b32_e32 v151, 0xffff0000, v194
	v_lshlrev_b32_e32 v152, 16, v195
	v_and_b32_e32 v153, 0xffff0000, v195
	v_pk_add_f32 v[150:151], v[66:67], v[150:151]
	v_pk_add_f32 v[152:153], v[68:69], v[152:153]
	s_nop 0
	v_mul_f32_e32 v150, 0xbfb8aa3b, v150
	v_mul_f32_e32 v151, 0xbfb8aa3b, v151
	v_mul_f32_e32 v152, 0xbfb8aa3b, v152
	v_mul_f32_e32 v153, 0xbfb8aa3b, v153
	v_exp_f32_e32 v150, v150
	v_exp_f32_e32 v151, v151
	v_exp_f32_e32 v152, v152
	v_exp_f32_e32 v153, v153
	v_add_f32_e32 v150, 1.0, v150
	v_add_f32_e32 v151, 1.0, v151
	v_add_f32_e32 v152, 1.0, v152
	v_add_f32_e32 v153, 1.0, v153
	v_rcp_f32_e32 v150, v150
	v_rcp_f32_e32 v151, v151
	v_rcp_f32_e32 v152, v152
	v_rcp_f32_e32 v153, v153
	v_pk_mul_f32 v[32:33], v[32:33], v[150:151]
	v_pk_mul_f32 v[34:35], v[34:35], v[152:153]
	s_nop 0
	global_store_dwordx4 v47, v[32:35], s[72:73] offset:192
	s_waitcnt vmcnt(7)
	v_lshlrev_b32_e32 v150, 16, v196
	v_and_b32_e32 v151, 0xffff0000, v196
	v_lshlrev_b32_e32 v152, 16, v197
	v_and_b32_e32 v153, 0xffff0000, v197
	v_pk_add_f32 v[150:151], v[54:55], v[150:151]
	v_pk_add_f32 v[152:153], v[56:57], v[152:153]
	s_nop 0
	v_mul_f32_e32 v150, 0xbfb8aa3b, v150
	v_mul_f32_e32 v151, 0xbfb8aa3b, v151
	v_mul_f32_e32 v152, 0xbfb8aa3b, v152
	v_mul_f32_e32 v153, 0xbfb8aa3b, v153
	v_exp_f32_e32 v150, v150
	v_exp_f32_e32 v151, v151
	v_exp_f32_e32 v152, v152
	v_exp_f32_e32 v153, v153
	v_add_f32_e32 v150, 1.0, v150
	v_add_f32_e32 v151, 1.0, v151
	v_add_f32_e32 v152, 1.0, v152
	v_add_f32_e32 v153, 1.0, v153
	v_rcp_f32_e32 v150, v150
	v_rcp_f32_e32 v151, v151
	v_rcp_f32_e32 v152, v152
	v_rcp_f32_e32 v153, v153
	v_pk_mul_f32 v[28:29], v[28:29], v[150:151]
	v_pk_mul_f32 v[30:31], v[30:31], v[152:153]
	s_nop 0
	global_store_dwordx4 v48, v[28:31], s[72:73] offset:0
	s_waitcnt vmcnt(6)
	v_lshlrev_b32_e32 v150, 16, v198
	v_and_b32_e32 v151, 0xffff0000, v198
	v_lshlrev_b32_e32 v152, 16, v199
	v_and_b32_e32 v153, 0xffff0000, v199
	v_pk_add_f32 v[150:151], v[58:59], v[150:151]
	v_pk_add_f32 v[152:153], v[60:61], v[152:153]
	s_nop 0
	v_mul_f32_e32 v150, 0xbfb8aa3b, v150
	v_mul_f32_e32 v151, 0xbfb8aa3b, v151
	v_mul_f32_e32 v152, 0xbfb8aa3b, v152
	v_mul_f32_e32 v153, 0xbfb8aa3b, v153
	v_exp_f32_e32 v150, v150
	v_exp_f32_e32 v151, v151
	v_exp_f32_e32 v152, v152
	v_exp_f32_e32 v153, v153
	v_add_f32_e32 v150, 1.0, v150
	v_add_f32_e32 v151, 1.0, v151
	v_add_f32_e32 v152, 1.0, v152
	v_add_f32_e32 v153, 1.0, v153
	v_rcp_f32_e32 v150, v150
	v_rcp_f32_e32 v151, v151
	v_rcp_f32_e32 v152, v152
	v_rcp_f32_e32 v153, v153
	v_pk_mul_f32 v[24:25], v[24:25], v[150:151]
	v_pk_mul_f32 v[26:27], v[26:27], v[152:153]
	s_nop 0
	global_store_dwordx4 v48, v[24:27], s[72:73] offset:64
	s_waitcnt vmcnt(5)
	v_lshlrev_b32_e32 v150, 16, v200
	v_and_b32_e32 v151, 0xffff0000, v200
	v_lshlrev_b32_e32 v152, 16, v201
	v_and_b32_e32 v153, 0xffff0000, v201
	v_pk_add_f32 v[150:151], v[62:63], v[150:151]
	v_pk_add_f32 v[152:153], v[64:65], v[152:153]
	s_nop 0
	v_mul_f32_e32 v150, 0xbfb8aa3b, v150
	v_mul_f32_e32 v151, 0xbfb8aa3b, v151
	v_mul_f32_e32 v152, 0xbfb8aa3b, v152
	v_mul_f32_e32 v153, 0xbfb8aa3b, v153
	v_exp_f32_e32 v150, v150
	v_exp_f32_e32 v151, v151
	v_exp_f32_e32 v152, v152
	v_exp_f32_e32 v153, v153
	v_add_f32_e32 v150, 1.0, v150
	v_add_f32_e32 v151, 1.0, v151
	v_add_f32_e32 v152, 1.0, v152
	v_add_f32_e32 v153, 1.0, v153
	v_rcp_f32_e32 v150, v150
	v_rcp_f32_e32 v151, v151
	v_rcp_f32_e32 v152, v152
	v_rcp_f32_e32 v153, v153
	v_pk_mul_f32 v[20:21], v[20:21], v[150:151]
	v_pk_mul_f32 v[22:23], v[22:23], v[152:153]
	s_nop 0
	global_store_dwordx4 v48, v[20:23], s[72:73] offset:128
	s_waitcnt vmcnt(4)
	v_lshlrev_b32_e32 v150, 16, v202
	v_and_b32_e32 v151, 0xffff0000, v202
	v_lshlrev_b32_e32 v152, 16, v203
	v_and_b32_e32 v153, 0xffff0000, v203
	v_pk_add_f32 v[150:151], v[66:67], v[150:151]
	v_pk_add_f32 v[152:153], v[68:69], v[152:153]
	s_nop 0
	v_mul_f32_e32 v150, 0xbfb8aa3b, v150
	v_mul_f32_e32 v151, 0xbfb8aa3b, v151
	v_mul_f32_e32 v152, 0xbfb8aa3b, v152
	v_mul_f32_e32 v153, 0xbfb8aa3b, v153
	v_exp_f32_e32 v150, v150
	v_exp_f32_e32 v151, v151
	v_exp_f32_e32 v152, v152
	v_exp_f32_e32 v153, v153
	v_add_f32_e32 v150, 1.0, v150
	v_add_f32_e32 v151, 1.0, v151
	v_add_f32_e32 v152, 1.0, v152
	v_add_f32_e32 v153, 1.0, v153
	v_rcp_f32_e32 v150, v150
	v_rcp_f32_e32 v151, v151
	v_rcp_f32_e32 v152, v152
	v_rcp_f32_e32 v153, v153
	v_pk_mul_f32 v[16:17], v[16:17], v[150:151]
	v_pk_mul_f32 v[18:19], v[18:19], v[152:153]
	s_nop 0
	global_store_dwordx4 v48, v[16:19], s[72:73] offset:192
	s_waitcnt vmcnt(3)
	v_lshlrev_b32_e32 v150, 16, v204
	v_and_b32_e32 v151, 0xffff0000, v204
	v_lshlrev_b32_e32 v152, 16, v205
	v_and_b32_e32 v153, 0xffff0000, v205
	v_pk_add_f32 v[150:151], v[54:55], v[150:151]
	v_pk_add_f32 v[152:153], v[56:57], v[152:153]
	s_nop 0
	v_mul_f32_e32 v150, 0xbfb8aa3b, v150
	v_mul_f32_e32 v151, 0xbfb8aa3b, v151
	v_mul_f32_e32 v152, 0xbfb8aa3b, v152
	v_mul_f32_e32 v153, 0xbfb8aa3b, v153
	v_exp_f32_e32 v150, v150
	v_exp_f32_e32 v151, v151
	v_exp_f32_e32 v152, v152
	v_exp_f32_e32 v153, v153
	v_add_f32_e32 v150, 1.0, v150
	v_add_f32_e32 v151, 1.0, v151
	v_add_f32_e32 v152, 1.0, v152
	v_add_f32_e32 v153, 1.0, v153
	v_rcp_f32_e32 v150, v150
	v_rcp_f32_e32 v151, v151
	v_rcp_f32_e32 v152, v152
	v_rcp_f32_e32 v153, v153
	v_pk_mul_f32 v[12:13], v[12:13], v[150:151]
	v_pk_mul_f32 v[14:15], v[14:15], v[152:153]
	s_nop 0
	global_store_dwordx4 v49, v[12:15], s[72:73] offset:0
	s_waitcnt vmcnt(2)
	v_lshlrev_b32_e32 v150, 16, v206
	v_and_b32_e32 v151, 0xffff0000, v206
	v_lshlrev_b32_e32 v152, 16, v207
	v_and_b32_e32 v153, 0xffff0000, v207
	v_pk_add_f32 v[150:151], v[58:59], v[150:151]
	v_pk_add_f32 v[152:153], v[60:61], v[152:153]
	s_nop 0
	v_mul_f32_e32 v150, 0xbfb8aa3b, v150
	v_mul_f32_e32 v151, 0xbfb8aa3b, v151
	v_mul_f32_e32 v152, 0xbfb8aa3b, v152
	v_mul_f32_e32 v153, 0xbfb8aa3b, v153
	v_exp_f32_e32 v150, v150
	v_exp_f32_e32 v151, v151
	v_exp_f32_e32 v152, v152
	v_exp_f32_e32 v153, v153
	v_add_f32_e32 v150, 1.0, v150
	v_add_f32_e32 v151, 1.0, v151
	v_add_f32_e32 v152, 1.0, v152
	v_add_f32_e32 v153, 1.0, v153
	v_rcp_f32_e32 v150, v150
	v_rcp_f32_e32 v151, v151
	v_rcp_f32_e32 v152, v152
	v_rcp_f32_e32 v153, v153
	v_pk_mul_f32 v[8:9], v[8:9], v[150:151]
	v_pk_mul_f32 v[10:11], v[10:11], v[152:153]
	s_nop 0
	global_store_dwordx4 v49, v[8:11], s[72:73] offset:64
	s_waitcnt vmcnt(1)
	v_lshlrev_b32_e32 v150, 16, v208
	v_and_b32_e32 v151, 0xffff0000, v208
	v_lshlrev_b32_e32 v152, 16, v209
	v_and_b32_e32 v153, 0xffff0000, v209
	v_pk_add_f32 v[150:151], v[62:63], v[150:151]
	v_pk_add_f32 v[152:153], v[64:65], v[152:153]
	s_nop 0
	v_mul_f32_e32 v150, 0xbfb8aa3b, v150
	v_mul_f32_e32 v151, 0xbfb8aa3b, v151
	v_mul_f32_e32 v152, 0xbfb8aa3b, v152
	v_mul_f32_e32 v153, 0xbfb8aa3b, v153
	v_exp_f32_e32 v150, v150
	v_exp_f32_e32 v151, v151
	v_exp_f32_e32 v152, v152
	v_exp_f32_e32 v153, v153
	v_add_f32_e32 v150, 1.0, v150
	v_add_f32_e32 v151, 1.0, v151
	v_add_f32_e32 v152, 1.0, v152
	v_add_f32_e32 v153, 1.0, v153
	v_rcp_f32_e32 v150, v150
	v_rcp_f32_e32 v151, v151
	v_rcp_f32_e32 v152, v152
	v_rcp_f32_e32 v153, v153
	v_pk_mul_f32 v[4:5], v[4:5], v[150:151]
	v_pk_mul_f32 v[6:7], v[6:7], v[152:153]
	s_nop 0
	global_store_dwordx4 v49, v[4:7], s[72:73] offset:128
	s_waitcnt vmcnt(0)
	v_lshlrev_b32_e32 v150, 16, v210
	v_and_b32_e32 v151, 0xffff0000, v210
	v_lshlrev_b32_e32 v152, 16, v211
	v_and_b32_e32 v153, 0xffff0000, v211
	v_pk_add_f32 v[150:151], v[66:67], v[150:151]
	v_pk_add_f32 v[152:153], v[68:69], v[152:153]
	s_nop 0
	v_mul_f32_e32 v150, 0xbfb8aa3b, v150
	v_mul_f32_e32 v151, 0xbfb8aa3b, v151
	v_mul_f32_e32 v152, 0xbfb8aa3b, v152
	v_mul_f32_e32 v153, 0xbfb8aa3b, v153
	v_exp_f32_e32 v150, v150
	v_exp_f32_e32 v151, v151
	v_exp_f32_e32 v152, v152
	v_exp_f32_e32 v153, v153
	v_add_f32_e32 v150, 1.0, v150
	v_add_f32_e32 v151, 1.0, v151
	v_add_f32_e32 v152, 1.0, v152
	v_add_f32_e32 v153, 1.0, v153
	v_rcp_f32_e32 v150, v150
	v_rcp_f32_e32 v151, v151
	v_rcp_f32_e32 v152, v152
	v_rcp_f32_e32 v153, v153
	v_pk_mul_f32 v[0:1], v[0:1], v[150:151]
	v_pk_mul_f32 v[2:3], v[2:3], v[152:153]
	s_nop 0
	global_store_dwordx4 v49, v[0:3], s[72:73] offset:192
	s_movk_i32 s4, 0x1c0
	s_nop 3
	s_add_i32 s2, s2, s4
	s_cmpk_gt_i32 s2, 0x57f
	s_cbranch_scc0 .LBB1_807
